# P6 epilogue without the lane exchange (64-byte store segments)
# speedup vs baseline: 1.0025x; 1.0001x over previous
.LBB0_783:
	s_lshl_b32 s98, s4, 8
	s_add_i32 s98, s98, s59
	s_lshl_b32 s98, s98, 13
	s_lshl_b32 s99, s5, 9
	s_add_u32 s98, s98, s99
	s_add_u32 s98, s98, s8
	s_add_u32 s98, s14, s98
	s_addc_u32 s99, s15, 0
	v_lshlrev_b32_e32 v148, 13, v1
	v_lshl_add_u32 v148, v150, 4, v148
	v_max_f32_e32 v122, 0, v122
	v_max_f32_e32 v123, 0, v123
	v_max_f32_e32 v124, 0, v124
	v_max_f32_e32 v125, 0, v125
	v_max_f32_e32 v126, 0, v126
	v_max_f32_e32 v127, 0, v127
	v_max_f32_e32 v128, 0, v128
	v_max_f32_e32 v129, 0, v129
	v_max_f32_e32 v114, 0, v114
	v_max_f32_e32 v115, 0, v115
	v_max_f32_e32 v116, 0, v116
	v_max_f32_e32 v117, 0, v117
	v_max_f32_e32 v118, 0, v118
	v_max_f32_e32 v119, 0, v119
	v_max_f32_e32 v120, 0, v120
	v_max_f32_e32 v121, 0, v121
	v_mul_f32_e32 v122, v122, v122
	v_mul_f32_e32 v123, v123, v123
	v_mul_f32_e32 v124, v124, v124
	v_mul_f32_e32 v125, v125, v125
	v_mul_f32_e32 v126, v126, v126
	v_mul_f32_e32 v127, v127, v127
	v_mul_f32_e32 v128, v128, v128
	v_mul_f32_e32 v129, v129, v129
	v_mul_f32_e32 v114, v114, v114
	v_mul_f32_e32 v115, v115, v115
	v_mul_f32_e32 v116, v116, v116
	v_mul_f32_e32 v117, v117, v117
	v_mul_f32_e32 v118, v118, v118
	v_mul_f32_e32 v119, v119, v119
	v_mul_f32_e32 v120, v120, v120
	v_mul_f32_e32 v121, v121, v121
	v_cvt_pk_bf16_f32 v126, v126, v127
	v_cvt_pk_bf16_f32 v127, v128, v129
	v_cvt_pk_bf16_f32 v128, v122, v123
	v_cvt_pk_bf16_f32 v129, v124, v125
	v_cvt_pk_bf16_f32 v118, v118, v119
	v_cvt_pk_bf16_f32 v119, v120, v121
	v_cvt_pk_bf16_f32 v120, v114, v115
	v_cvt_pk_bf16_f32 v121, v116, v117
	global_store_dwordx4 v148, v[126:129], s[98:99] nt
	global_store_dwordx4 v148, v[118:121], s[98:99] offset:64 nt
	v_max_f32_e32 v106, 0, v106
	v_max_f32_e32 v107, 0, v107
	v_max_f32_e32 v108, 0, v108
	v_max_f32_e32 v109, 0, v109
	v_max_f32_e32 v110, 0, v110
	v_max_f32_e32 v111, 0, v111
	v_max_f32_e32 v112, 0, v112
	v_max_f32_e32 v113, 0, v113
	v_max_f32_e32 v98, 0, v98
	v_max_f32_e32 v99, 0, v99
	v_max_f32_e32 v100, 0, v100
	v_max_f32_e32 v101, 0, v101
	v_max_f32_e32 v102, 0, v102
	v_max_f32_e32 v103, 0, v103
	v_max_f32_e32 v104, 0, v104
	v_max_f32_e32 v105, 0, v105
	v_mul_f32_e32 v106, v106, v106
	v_mul_f32_e32 v107, v107, v107
	v_mul_f32_e32 v108, v108, v108
	v_mul_f32_e32 v109, v109, v109
	v_mul_f32_e32 v110, v110, v110
	v_mul_f32_e32 v111, v111, v111
	v_mul_f32_e32 v112, v112, v112
	v_mul_f32_e32 v113, v113, v113
	v_mul_f32_e32 v98, v98, v98
	v_mul_f32_e32 v99, v99, v99
	v_mul_f32_e32 v100, v100, v100
	v_mul_f32_e32 v101, v101, v101
	v_mul_f32_e32 v102, v102, v102
	v_mul_f32_e32 v103, v103, v103
	v_mul_f32_e32 v104, v104, v104
	v_mul_f32_e32 v105, v105, v105
	v_cvt_pk_bf16_f32 v110, v110, v111
	v_cvt_pk_bf16_f32 v111, v112, v113
	v_cvt_pk_bf16_f32 v112, v106, v107
	v_cvt_pk_bf16_f32 v113, v108, v109
	v_cvt_pk_bf16_f32 v102, v102, v103
	v_cvt_pk_bf16_f32 v103, v104, v105
	v_cvt_pk_bf16_f32 v104, v98, v99
	v_cvt_pk_bf16_f32 v105, v100, v101
	s_add_u32 s98, s98, 0x20000
	s_addc_u32 s99, s99, 0
	global_store_dwordx4 v148, v[110:113], s[98:99] nt
	global_store_dwordx4 v148, v[102:105], s[98:99] offset:64 nt
	v_max_f32_e32 v90, 0, v90
	v_max_f32_e32 v91, 0, v91
	v_max_f32_e32 v92, 0, v92
	v_max_f32_e32 v93, 0, v93
	v_max_f32_e32 v94, 0, v94
	v_max_f32_e32 v95, 0, v95
	v_max_f32_e32 v96, 0, v96
	v_max_f32_e32 v97, 0, v97
	v_max_f32_e32 v82, 0, v82
	v_max_f32_e32 v83, 0, v83
	v_max_f32_e32 v84, 0, v84
	v_max_f32_e32 v85, 0, v85
	v_max_f32_e32 v86, 0, v86
	v_max_f32_e32 v87, 0, v87
	v_max_f32_e32 v88, 0, v88
	v_max_f32_e32 v89, 0, v89
	v_mul_f32_e32 v90, v90, v90
	v_mul_f32_e32 v91, v91, v91
	v_mul_f32_e32 v92, v92, v92
	v_mul_f32_e32 v93, v93, v93
	v_mul_f32_e32 v94, v94, v94
	v_mul_f32_e32 v95, v95, v95
	v_mul_f32_e32 v96, v96, v96
	v_mul_f32_e32 v97, v97, v97
	v_mul_f32_e32 v82, v82, v82
	v_mul_f32_e32 v83, v83, v83
	v_mul_f32_e32 v84, v84, v84
	v_mul_f32_e32 v85, v85, v85
	v_mul_f32_e32 v86, v86, v86
	v_mul_f32_e32 v87, v87, v87
	v_mul_f32_e32 v88, v88, v88
	v_mul_f32_e32 v89, v89, v89
	v_cvt_pk_bf16_f32 v94, v94, v95
	v_cvt_pk_bf16_f32 v95, v96, v97
	v_cvt_pk_bf16_f32 v96, v90, v91
	v_cvt_pk_bf16_f32 v97, v92, v93
	v_cvt_pk_bf16_f32 v86, v86, v87
	v_cvt_pk_bf16_f32 v87, v88, v89
	v_cvt_pk_bf16_f32 v88, v82, v83
	v_cvt_pk_bf16_f32 v89, v84, v85
	s_add_u32 s98, s98, 0x20000
	s_addc_u32 s99, s99, 0
	global_store_dwordx4 v148, v[94:97], s[98:99] nt
	global_store_dwordx4 v148, v[86:89], s[98:99] offset:64 nt
	v_max_f32_e32 v74, 0, v74
	v_max_f32_e32 v75, 0, v75
	v_max_f32_e32 v76, 0, v76
	v_max_f32_e32 v77, 0, v77
	v_max_f32_e32 v78, 0, v78
	v_max_f32_e32 v79, 0, v79
	v_max_f32_e32 v80, 0, v80
	v_max_f32_e32 v81, 0, v81
	v_max_f32_e32 v66, 0, v66
	v_max_f32_e32 v67, 0, v67
	v_max_f32_e32 v68, 0, v68
	v_max_f32_e32 v69, 0, v69
	v_max_f32_e32 v70, 0, v70
	v_max_f32_e32 v71, 0, v71
	v_max_f32_e32 v72, 0, v72
	v_max_f32_e32 v73, 0, v73
	v_mul_f32_e32 v74, v74, v74
	v_mul_f32_e32 v75, v75, v75
	v_mul_f32_e32 v76, v76, v76
	v_mul_f32_e32 v77, v77, v77
	v_mul_f32_e32 v78, v78, v78
	v_mul_f32_e32 v79, v79, v79
	v_mul_f32_e32 v80, v80, v80
	v_mul_f32_e32 v81, v81, v81
	v_mul_f32_e32 v66, v66, v66
	v_mul_f32_e32 v67, v67, v67
	v_mul_f32_e32 v68, v68, v68
	v_mul_f32_e32 v69, v69, v69
	v_mul_f32_e32 v70, v70, v70
	v_mul_f32_e32 v71, v71, v71
	v_mul_f32_e32 v72, v72, v72
	v_mul_f32_e32 v73, v73, v73
	v_cvt_pk_bf16_f32 v78, v78, v79
	v_cvt_pk_bf16_f32 v79, v80, v81
	v_cvt_pk_bf16_f32 v80, v74, v75
	v_cvt_pk_bf16_f32 v81, v76, v77
	v_cvt_pk_bf16_f32 v70, v70, v71
	v_cvt_pk_bf16_f32 v71, v72, v73
	v_cvt_pk_bf16_f32 v72, v66, v67
	v_cvt_pk_bf16_f32 v73, v68, v69
	s_add_u32 s98, s98, 0x20000
	s_addc_u32 s99, s99, 0
	global_store_dwordx4 v148, v[78:81], s[98:99] nt
	global_store_dwordx4 v148, v[70:73], s[98:99] offset:64 nt
	v_max_f32_e32 v58, 0, v58
	v_max_f32_e32 v59, 0, v59
	v_max_f32_e32 v60, 0, v60
	v_max_f32_e32 v61, 0, v61
	v_max_f32_e32 v62, 0, v62
	v_max_f32_e32 v63, 0, v63
	v_max_f32_e32 v64, 0, v64
	v_max_f32_e32 v65, 0, v65
	v_max_f32_e32 v50, 0, v50
	v_max_f32_e32 v51, 0, v51
	v_max_f32_e32 v52, 0, v52
	v_max_f32_e32 v53, 0, v53
	v_max_f32_e32 v54, 0, v54
	v_max_f32_e32 v55, 0, v55
	v_max_f32_e32 v56, 0, v56
	v_max_f32_e32 v57, 0, v57
	v_mul_f32_e32 v58, v58, v58
	v_mul_f32_e32 v59, v59, v59
	v_mul_f32_e32 v60, v60, v60
	v_mul_f32_e32 v61, v61, v61
	v_mul_f32_e32 v62, v62, v62
	v_mul_f32_e32 v63, v63, v63
	v_mul_f32_e32 v64, v64, v64
	v_mul_f32_e32 v65, v65, v65
	v_mul_f32_e32 v50, v50, v50
	v_mul_f32_e32 v51, v51, v51
	v_mul_f32_e32 v52, v52, v52
	v_mul_f32_e32 v53, v53, v53
	v_mul_f32_e32 v54, v54, v54
	v_mul_f32_e32 v55, v55, v55
	v_mul_f32_e32 v56, v56, v56
	v_mul_f32_e32 v57, v57, v57
	v_cvt_pk_bf16_f32 v62, v62, v63
	v_cvt_pk_bf16_f32 v63, v64, v65
	v_cvt_pk_bf16_f32 v64, v58, v59
	v_cvt_pk_bf16_f32 v65, v60, v61
	v_cvt_pk_bf16_f32 v54, v54, v55
	v_cvt_pk_bf16_f32 v55, v56, v57
	v_cvt_pk_bf16_f32 v56, v50, v51
	v_cvt_pk_bf16_f32 v57, v52, v53
	s_add_u32 s98, s98, 0xa0000
	s_addc_u32 s99, s99, 0
	global_store_dwordx4 v148, v[62:65], s[98:99] nt
	global_store_dwordx4 v148, v[54:57], s[98:99] offset:64 nt
	v_max_f32_e32 v42, 0, v42
	v_max_f32_e32 v43, 0, v43
	v_max_f32_e32 v44, 0, v44
	v_max_f32_e32 v45, 0, v45
	v_max_f32_e32 v46, 0, v46
	v_max_f32_e32 v47, 0, v47
	v_max_f32_e32 v48, 0, v48
	v_max_f32_e32 v49, 0, v49
	v_max_f32_e32 v34, 0, v34
	v_max_f32_e32 v35, 0, v35
	v_max_f32_e32 v36, 0, v36
	v_max_f32_e32 v37, 0, v37
	v_max_f32_e32 v38, 0, v38
	v_max_f32_e32 v39, 0, v39
	v_max_f32_e32 v40, 0, v40
	v_max_f32_e32 v41, 0, v41
	v_mul_f32_e32 v42, v42, v42
	v_mul_f32_e32 v43, v43, v43
	v_mul_f32_e32 v44, v44, v44
	v_mul_f32_e32 v45, v45, v45
	v_mul_f32_e32 v46, v46, v46
	v_mul_f32_e32 v47, v47, v47
	v_mul_f32_e32 v48, v48, v48
	v_mul_f32_e32 v49, v49, v49
	v_mul_f32_e32 v34, v34, v34
	v_mul_f32_e32 v35, v35, v35
	v_mul_f32_e32 v36, v36, v36
	v_mul_f32_e32 v37, v37, v37
	v_mul_f32_e32 v38, v38, v38
	v_mul_f32_e32 v39, v39, v39
	v_mul_f32_e32 v40, v40, v40
	v_mul_f32_e32 v41, v41, v41
	v_cvt_pk_bf16_f32 v46, v46, v47
	v_cvt_pk_bf16_f32 v47, v48, v49
	v_cvt_pk_bf16_f32 v48, v42, v43
	v_cvt_pk_bf16_f32 v49, v44, v45
	v_cvt_pk_bf16_f32 v38, v38, v39
	v_cvt_pk_bf16_f32 v39, v40, v41
	v_cvt_pk_bf16_f32 v40, v34, v35
	v_cvt_pk_bf16_f32 v41, v36, v37
	s_add_u32 s98, s98, 0x20000
	s_addc_u32 s99, s99, 0
	global_store_dwordx4 v148, v[46:49], s[98:99] nt
	global_store_dwordx4 v148, v[38:41], s[98:99] offset:64 nt
	v_max_f32_e32 v26, 0, v26
	v_max_f32_e32 v27, 0, v27
	v_max_f32_e32 v28, 0, v28
	v_max_f32_e32 v29, 0, v29
	v_max_f32_e32 v30, 0, v30
	v_max_f32_e32 v31, 0, v31
	v_max_f32_e32 v32, 0, v32
	v_max_f32_e32 v33, 0, v33
	v_max_f32_e32 v18, 0, v18
	v_max_f32_e32 v19, 0, v19
	v_max_f32_e32 v20, 0, v20
	v_max_f32_e32 v21, 0, v21
	v_max_f32_e32 v22, 0, v22
	v_max_f32_e32 v23, 0, v23
	v_max_f32_e32 v24, 0, v24
	v_max_f32_e32 v25, 0, v25
	v_mul_f32_e32 v26, v26, v26
	v_mul_f32_e32 v27, v27, v27
	v_mul_f32_e32 v28, v28, v28
	v_mul_f32_e32 v29, v29, v29
	v_mul_f32_e32 v30, v30, v30
	v_mul_f32_e32 v31, v31, v31
	v_mul_f32_e32 v32, v32, v32
	v_mul_f32_e32 v33, v33, v33
	v_mul_f32_e32 v18, v18, v18
	v_mul_f32_e32 v19, v19, v19
	v_mul_f32_e32 v20, v20, v20
	v_mul_f32_e32 v21, v21, v21
	v_mul_f32_e32 v22, v22, v22
	v_mul_f32_e32 v23, v23, v23
	v_mul_f32_e32 v24, v24, v24
	v_mul_f32_e32 v25, v25, v25
	v_cvt_pk_bf16_f32 v30, v30, v31
	v_cvt_pk_bf16_f32 v31, v32, v33
	v_cvt_pk_bf16_f32 v32, v26, v27
	v_cvt_pk_bf16_f32 v33, v28, v29
	v_cvt_pk_bf16_f32 v22, v22, v23
	v_cvt_pk_bf16_f32 v23, v24, v25
	v_cvt_pk_bf16_f32 v24, v18, v19
	v_cvt_pk_bf16_f32 v25, v20, v21
	s_add_u32 s98, s98, 0x20000
	s_addc_u32 s99, s99, 0
	global_store_dwordx4 v148, v[30:33], s[98:99] nt
	global_store_dwordx4 v148, v[22:25], s[98:99] offset:64 nt
	v_max_f32_e32 v10, 0, v10
	v_max_f32_e32 v11, 0, v11
	v_max_f32_e32 v12, 0, v12
	v_max_f32_e32 v13, 0, v13
	v_max_f32_e32 v14, 0, v14
	v_max_f32_e32 v15, 0, v15
	v_max_f32_e32 v16, 0, v16
	v_max_f32_e32 v17, 0, v17
	v_max_f32_e32 v2, 0, v2
	v_max_f32_e32 v3, 0, v3
	v_max_f32_e32 v4, 0, v4
	v_max_f32_e32 v5, 0, v5
	v_max_f32_e32 v6, 0, v6
	v_max_f32_e32 v7, 0, v7
	v_max_f32_e32 v8, 0, v8
	v_max_f32_e32 v9, 0, v9
	v_mul_f32_e32 v10, v10, v10
	v_mul_f32_e32 v11, v11, v11
	v_mul_f32_e32 v12, v12, v12
	v_mul_f32_e32 v13, v13, v13
	v_mul_f32_e32 v14, v14, v14
	v_mul_f32_e32 v15, v15, v15
	v_mul_f32_e32 v16, v16, v16
	v_mul_f32_e32 v17, v17, v17
	v_mul_f32_e32 v2, v2, v2
	v_mul_f32_e32 v3, v3, v3
	v_mul_f32_e32 v4, v4, v4
	v_mul_f32_e32 v5, v5, v5
	v_mul_f32_e32 v6, v6, v6
	v_mul_f32_e32 v7, v7, v7
	v_mul_f32_e32 v8, v8, v8
	v_mul_f32_e32 v9, v9, v9
	v_cvt_pk_bf16_f32 v14, v14, v15
	v_cvt_pk_bf16_f32 v15, v16, v17
	v_cvt_pk_bf16_f32 v16, v10, v11
	v_cvt_pk_bf16_f32 v17, v12, v13
	v_cvt_pk_bf16_f32 v6, v6, v7
	v_cvt_pk_bf16_f32 v7, v8, v9
	v_cvt_pk_bf16_f32 v8, v2, v3
	v_cvt_pk_bf16_f32 v9, v4, v5
	s_add_u32 s98, s98, 0x20000
	s_addc_u32 s99, s99, 0
	global_store_dwordx4 v148, v[14:17], s[98:99] nt
	global_store_dwordx4 v148, v[6:9], s[98:99] offset:64 nt
	s_andn2_b64 vcc, exec, s[0:1]
	s_mov_b64 s[0:1], -1
	s_mov_b32 s98, 1
	s_cbranch_vccnz .LBB0_772
	s_andn2_b64 vcc, exec, s[10:11]
	s_cbranch_vccnz .LBB0_771
	s_barrier
	s_branch .LBB0_771
